# gating MFMA pass: fragment reads per quarter up front, MFMAs interleaved over d-frags, paired dwordx4 O stores
# speedup vs baseline: 1.0029x; 1.0029x over previous
.LBB0_506:
	s_add_i32 s88, s88, 1
	s_add_u32 s74, s74, 0x200
	s_addc_u32 s75, s75, 0
	s_mov_b64 s[68:69], 0x10000
	v_lshl_add_u64 v[96:97], v[96:97], 0, s[82:83]
	v_lshl_add_u64 v[98:99], v[98:99], 0, s[82:83]
	v_lshl_add_u64 v[100:101], v[100:101], 0, s[82:83]
	s_cmpk_lg_i32 s74, 0x800
	v_lshl_add_u64 v[104:105], v[104:105], 0, s[68:69]
	s_cbranch_scc0 .LBB0_570

.LBB0_522:
	s_waitcnt vmcnt(9)
	v_cndmask_b32_e64 v80, v80, 0, s[2:3]
	v_bfe_u32 v138, v80, 16, 1
	v_cndmask_b32_e64 v81, 0, v81, s[4:5]
	v_add3_u32 v80, v80, v138, s85
	v_bfe_u32 v138, v81, 16, 1
	v_lshrrev_b32_e32 v80, 16, v80
	v_add3_u32 v81, v81, v138, s85
	v_and_or_b32 v80, v81, s84, v80
	v_cndmask_b32_e64 v81, v82, 0, s[6:7]
	v_bfe_u32 v82, v81, 16, 1
	v_add3_u32 v81, v81, v82, s85
	v_cndmask_b32_e64 v82, v83, 0, s[8:9]
	v_bfe_u32 v83, v82, 16, 1
	v_add_u32_e32 v141, s89, v129
	v_lshrrev_b32_e32 v81, 16, v81
	v_add3_u32 v82, v82, v83, s85
	v_cndmask_b32_e64 v72, v72, 0, s[10:11]
	v_add_u32_e32 v138, v141, v130
	v_and_or_b32 v81, v82, s84, v81
	v_bfe_u32 v82, v72, 16, 1
	v_cndmask_b32_e64 v73, v73, 0, s[12:13]
	v_add3_u32 v72, v72, v82, s85
	v_bfe_u32 v82, v73, 16, 1
	v_lshrrev_b32_e32 v72, 16, v72
	v_add3_u32 v73, v73, v82, s85
	v_and_or_b32 v82, v73, s84, v72
	v_cndmask_b32_e64 v72, v74, 0, s[14:15]
	v_bfe_u32 v73, v72, 16, 1
	v_add3_u32 v72, v72, v73, s85
	v_cndmask_b32_e64 v73, v75, 0, s[16:17]
	v_bfe_u32 v74, v73, 16, 1
	v_lshrrev_b32_e32 v72, 16, v72
	v_add3_u32 v73, v73, v74, s85
	v_and_or_b32 v83, v73, s84, v72
	v_add_u32_e32 v150, v141, v131
	v_add_u32_e32 v151, v141, v132
	v_add_u32_e32 v152, v141, v133
	v_add_u32_e32 v153, v141, v134
	v_add_u32_e32 v154, v141, v128
	v_add_u32_e32 v155, v141, v135
	v_add_u32_e32 v156, v141, v136
	ds_read_b128 v[160:163], v138
	ds_read_b128 v[164:167], v138 offset:64
	ds_read_b128 v[168:171], v138 offset:128
	ds_read_b128 v[172:175], v138 offset:192
	ds_read_b128 v[176:179], v150 offset:4352
	ds_read_b128 v[180:183], v150 offset:4416
	ds_read_b128 v[184:187], v150 offset:4480
	ds_read_b128 v[188:191], v150 offset:4544
	ds_read_b128 v[192:195], v151 offset:8704
	ds_read_b128 v[196:199], v152 offset:8704
	ds_read_b128 v[200:203], v151 offset:8832
	ds_read_b128 v[204:207], v153 offset:8704
	ds_read_b128 v[208:211], v154 offset:13056
	ds_read_b128 v[212:215], v155 offset:13056
	ds_read_b128 v[216:219], v154 offset:13184
	ds_read_b128 v[220:223], v156 offset:13056
	v_mbcnt_lo_u32_b32 v148, -1, 0
	v_mbcnt_hi_u32_b32 v148, -1, v148
	v_lshrrev_b32_e32 v148, 4, v148
	v_and_b32_e32 v148, 1, v148
	v_mul_u32_u24_e32 v148, 24, v148
	v_mov_b32_e32 v149, 0
	v_lshl_add_u64 v[158:159], v[96:97], 0, s[0:1]
	v_lshl_add_u64 v[158:159], v[158:159], 0, v[148:149]
	s_waitcnt lgkmcnt(8)
	v_mfma_f32_16x16x32_bf16 v[224:227], v[160:163], v[80:83], 0
	v_mfma_f32_16x16x32_bf16 v[228:231], v[176:179], v[80:83], 0
	v_mfma_f32_16x16x32_bf16 v[224:227], v[164:167], v[76:79], v[224:227]
	v_mfma_f32_16x16x32_bf16 v[228:231], v[180:183], v[76:79], v[228:231]
	v_mfma_f32_16x16x32_bf16 v[224:227], v[168:171], v[84:87], v[224:227]
	v_mfma_f32_16x16x32_bf16 v[228:231], v[184:187], v[84:87], v[228:231]
	v_mfma_f32_16x16x32_bf16 v[224:227], v[172:175], v[88:91], v[224:227]
	v_mfma_f32_16x16x32_bf16 v[228:231], v[188:191], v[88:91], v[228:231]
	ds_read_b128 v[160:163], v138 offset:17408
	ds_read_b128 v[164:167], v138 offset:17472
	ds_read_b128 v[168:171], v138 offset:17536
	ds_read_b128 v[172:175], v138 offset:17600
	ds_read_b128 v[176:179], v150 offset:21760
	ds_read_b128 v[180:183], v150 offset:21824
	ds_read_b128 v[184:187], v150 offset:21888
	ds_read_b128 v[188:191], v150 offset:21952
	s_waitcnt lgkmcnt(8)
	v_mfma_f32_16x16x32_bf16 v[232:235], v[192:195], v[80:83], 0
	v_mfma_f32_16x16x32_bf16 v[236:239], v[208:211], v[80:83], 0
	v_mfma_f32_16x16x32_bf16 v[232:235], v[196:199], v[76:79], v[232:235]
	v_mfma_f32_16x16x32_bf16 v[236:239], v[212:215], v[76:79], v[236:239]
	v_mfma_f32_16x16x32_bf16 v[232:235], v[200:203], v[84:87], v[232:235]
	v_mfma_f32_16x16x32_bf16 v[236:239], v[216:219], v[84:87], v[236:239]
	v_mfma_f32_16x16x32_bf16 v[232:235], v[204:207], v[88:91], v[232:235]
	v_mfma_f32_16x16x32_bf16 v[236:239], v[220:223], v[88:91], v[236:239]
	ds_read_b128 v[192:195], v151 offset:26112
	ds_read_b128 v[196:199], v152 offset:26112
	ds_read_b128 v[200:203], v151 offset:26240
	ds_read_b128 v[204:207], v153 offset:26112
	ds_read_b128 v[208:211], v154 offset:30464
	ds_read_b128 v[212:215], v155 offset:30464
	ds_read_b128 v[216:219], v154 offset:30592
	ds_read_b128 v[220:223], v156 offset:30464
	s_waitcnt vmcnt(6)
	v_lshlrev_b32_e32 v248, 16, v122
	v_add_f32_e32 v249, v137, v224
	v_mul_f32_e32 v249, v249, v248
	v_and_b32_e32 v248, 0xffff0000, v122
	v_add_f32_e32 v250, v137, v225
	v_mul_f32_e32 v250, v250, v248
	v_cvt_pk_bf16_f32 v240, v249, v250
	v_lshlrev_b32_e32 v248, 16, v123
	v_add_f32_e32 v249, v137, v226
	v_mul_f32_e32 v249, v249, v248
	v_and_b32_e32 v248, 0xffff0000, v123
	v_add_f32_e32 v250, v137, v227
	v_mul_f32_e32 v250, v250, v248
	v_cvt_pk_bf16_f32 v241, v249, v250
	v_lshlrev_b32_e32 v248, 16, v120
	v_add_f32_e32 v249, v137, v228
	v_mul_f32_e32 v249, v249, v248
	v_and_b32_e32 v248, 0xffff0000, v120
	v_add_f32_e32 v250, v137, v229
	v_mul_f32_e32 v250, v250, v248
	v_cvt_pk_bf16_f32 v242, v249, v250
	v_lshlrev_b32_e32 v248, 16, v121
	v_add_f32_e32 v249, v137, v230
	v_mul_f32_e32 v249, v249, v248
	v_and_b32_e32 v248, 0xffff0000, v121
	v_add_f32_e32 v250, v137, v231
	v_mul_f32_e32 v250, v250, v248
	v_cvt_pk_bf16_f32 v243, v249, v250
	s_nop 1
	v_permlane16_swap_b32_e32 v240, v242
	v_permlane16_swap_b32_e32 v241, v243
	global_store_dwordx4 v[158:159], v[240:243], off offset:-128
	s_waitcnt lgkmcnt(8)
	v_mfma_f32_16x16x32_bf16 v[224:227], v[160:163], v[80:83], 0
	v_mfma_f32_16x16x32_bf16 v[228:231], v[176:179], v[80:83], 0
	v_mfma_f32_16x16x32_bf16 v[224:227], v[164:167], v[76:79], v[224:227]
	v_mfma_f32_16x16x32_bf16 v[228:231], v[180:183], v[76:79], v[228:231]
	v_mfma_f32_16x16x32_bf16 v[224:227], v[168:171], v[84:87], v[224:227]
	v_mfma_f32_16x16x32_bf16 v[228:231], v[184:187], v[84:87], v[228:231]
	v_mfma_f32_16x16x32_bf16 v[224:227], v[172:175], v[88:91], v[224:227]
	v_mfma_f32_16x16x32_bf16 v[228:231], v[188:191], v[88:91], v[228:231]
	s_waitcnt vmcnt(5)
	v_lshlrev_b32_e32 v248, 16, v118
	v_add_f32_e32 v249, v137, v232
	v_mul_f32_e32 v249, v249, v248
	v_and_b32_e32 v248, 0xffff0000, v118
	v_add_f32_e32 v250, v137, v233
	v_mul_f32_e32 v250, v250, v248
	v_cvt_pk_bf16_f32 v244, v249, v250
	v_lshlrev_b32_e32 v248, 16, v119
	v_add_f32_e32 v249, v137, v234
	v_mul_f32_e32 v249, v249, v248
	v_and_b32_e32 v248, 0xffff0000, v119
	v_add_f32_e32 v250, v137, v235
	v_mul_f32_e32 v250, v250, v248
	v_cvt_pk_bf16_f32 v245, v249, v250
	v_lshlrev_b32_e32 v248, 16, v116
	v_add_f32_e32 v249, v137, v236
	v_mul_f32_e32 v249, v249, v248
	v_and_b32_e32 v248, 0xffff0000, v116
	v_add_f32_e32 v250, v137, v237
	v_mul_f32_e32 v250, v250, v248
	v_cvt_pk_bf16_f32 v246, v249, v250
	v_lshlrev_b32_e32 v248, 16, v117
	v_add_f32_e32 v249, v137, v238
	v_mul_f32_e32 v249, v249, v248
	v_and_b32_e32 v248, 0xffff0000, v117
	v_add_f32_e32 v250, v137, v239
	v_mul_f32_e32 v250, v250, v248
	v_cvt_pk_bf16_f32 v247, v249, v250
	s_nop 1
	v_permlane16_swap_b32_e32 v244, v246
	v_permlane16_swap_b32_e32 v245, v247
	global_store_dwordx4 v[158:159], v[244:247], off offset:-64
	s_waitcnt lgkmcnt(0)
	v_mfma_f32_16x16x32_bf16 v[232:235], v[192:195], v[80:83], 0
	v_mfma_f32_16x16x32_bf16 v[236:239], v[208:211], v[80:83], 0
	v_mfma_f32_16x16x32_bf16 v[232:235], v[196:199], v[76:79], v[232:235]
	v_mfma_f32_16x16x32_bf16 v[236:239], v[212:215], v[76:79], v[236:239]
	v_mfma_f32_16x16x32_bf16 v[232:235], v[200:203], v[84:87], v[232:235]
	v_mfma_f32_16x16x32_bf16 v[236:239], v[216:219], v[84:87], v[236:239]
	v_mfma_f32_16x16x32_bf16 v[232:235], v[204:207], v[88:91], v[232:235]
	v_mfma_f32_16x16x32_bf16 v[236:239], v[220:223], v[88:91], v[236:239]
	s_waitcnt vmcnt(4)
	v_lshlrev_b32_e32 v248, 16, v114
	v_add_f32_e32 v249, v137, v224
	v_mul_f32_e32 v249, v249, v248
	v_and_b32_e32 v248, 0xffff0000, v114
	v_add_f32_e32 v250, v137, v225
	v_mul_f32_e32 v250, v250, v248
	v_cvt_pk_bf16_f32 v240, v249, v250
	v_lshlrev_b32_e32 v248, 16, v115
	v_add_f32_e32 v249, v137, v226
	v_mul_f32_e32 v249, v249, v248
	v_and_b32_e32 v248, 0xffff0000, v115
	v_add_f32_e32 v250, v137, v227
	v_mul_f32_e32 v250, v250, v248
	v_cvt_pk_bf16_f32 v241, v249, v250
	v_lshlrev_b32_e32 v248, 16, v112
	v_add_f32_e32 v249, v137, v228
	v_mul_f32_e32 v249, v249, v248
	v_and_b32_e32 v248, 0xffff0000, v112
	v_add_f32_e32 v250, v137, v229
	v_mul_f32_e32 v250, v250, v248
	v_cvt_pk_bf16_f32 v242, v249, v250
	v_lshlrev_b32_e32 v248, 16, v113
	v_add_f32_e32 v249, v137, v230
	v_mul_f32_e32 v249, v249, v248
	v_and_b32_e32 v248, 0xffff0000, v113
	v_add_f32_e32 v250, v137, v231
	v_mul_f32_e32 v250, v250, v248
	v_cvt_pk_bf16_f32 v243, v249, v250
	s_nop 1
	v_permlane16_swap_b32_e32 v240, v242
	v_permlane16_swap_b32_e32 v241, v243
	global_store_dwordx4 v[158:159], v[240:243], off offset:0
	s_nop 7
	s_nop 7
	s_waitcnt vmcnt(3)
	v_lshlrev_b32_e32 v248, 16, v110
	v_add_f32_e32 v249, v137, v232
	v_mul_f32_e32 v249, v249, v248
	v_and_b32_e32 v248, 0xffff0000, v110
	v_add_f32_e32 v250, v137, v233
	v_mul_f32_e32 v250, v250, v248
	v_cvt_pk_bf16_f32 v244, v249, v250
	v_lshlrev_b32_e32 v248, 16, v111
	v_add_f32_e32 v249, v137, v234
	v_mul_f32_e32 v249, v249, v248
	v_and_b32_e32 v248, 0xffff0000, v111
	v_add_f32_e32 v250, v137, v235
	v_mul_f32_e32 v250, v250, v248
	v_cvt_pk_bf16_f32 v245, v249, v250
	v_lshlrev_b32_e32 v248, 16, v108
	v_add_f32_e32 v249, v137, v236
	v_mul_f32_e32 v249, v249, v248
	v_and_b32_e32 v248, 0xffff0000, v108
	v_add_f32_e32 v250, v137, v237
	v_mul_f32_e32 v250, v250, v248
	v_cvt_pk_bf16_f32 v246, v249, v250
	v_lshlrev_b32_e32 v248, 16, v109
	v_add_f32_e32 v249, v137, v238
	v_mul_f32_e32 v249, v249, v248
	v_and_b32_e32 v248, 0xffff0000, v109
	v_add_f32_e32 v250, v137, v239
	v_mul_f32_e32 v250, v250, v248
	v_cvt_pk_bf16_f32 v247, v249, v250
	s_nop 1
	v_permlane16_swap_b32_e32 v244, v246
	v_permlane16_swap_b32_e32 v245, v247
	global_store_dwordx4 v[158:159], v[244:247], off offset:64
	s_branch .LBB0_506
